# P1 epilogue: the 8 rstd row-scale loads of a unit issued together at epilogue start (were load + vmcnt(0) per row group), on top of the 24-bit address multiply
# speedup vs baseline: 1.0094x; 1.0094x over previous
;     DI void operator()(const pg8::f32x4 (&acc)[2][2][4][2], const pg8::Unit& u, int wr, int wc, int fr, int fq) const {
;     ...
;         for (int ai = 0; ai < 2; ++ai)
; #pragma unroll
;             for (int m = 0; m < 4; ++m) {
;                 const int tok = u.pm * 256 + ai * 128 + wr * 64 + m * 16 + fr;
;                 const float rs = rstd[tok];
;                 const float rsq = split == 0 ? rs * (0.125f * 1.4426950408889634f) : rs;
;                 const int pos = 16 + (tok & 4095), b = tok >> 12, s = tok & 4095;
; #pragma unroll
;                 for (int bj = 0; bj < 2; ++bj) {
;                     const int nb = nc0 + bj * 128 + wc * 32 + 8 * fq;
;                     float v[8];
; #pragma unroll
;                     for (int j = 0; j < 4; ++j) { v[j] = acc[ai][bj][m][0][j] * rsq; v[4 + j] = acc[ai][bj][m][1][j] * rsq; }
.LBB0_299:
	s_lshl_b32 s74, s4, 8
	s_add_i32 s74, s74, s94
	v_or_b32_e32 v248, s74, v167
	v_ashrrev_i32_e32 v249, 31, v248
	v_lshl_add_u64 v[250:251], v[248:249], 2, s[20:21]
	global_load_dword v240, v[250:251], off
	v_or_b32_e32 v248, s74, v171
	v_ashrrev_i32_e32 v249, 31, v248
	v_lshl_add_u64 v[252:253], v[248:249], 2, s[20:21]
	global_load_dword v241, v[252:253], off
	v_or_b32_e32 v248, s74, v172
	v_ashrrev_i32_e32 v249, 31, v248
	v_lshl_add_u64 v[250:251], v[248:249], 2, s[20:21]
	global_load_dword v242, v[250:251], off
	v_or_b32_e32 v248, s74, v173
	v_ashrrev_i32_e32 v249, 31, v248
	v_lshl_add_u64 v[252:253], v[248:249], 2, s[20:21]
	global_load_dword v243, v[252:253], off
	s_add_i32 s98, s74, 0x80
	v_or_b32_e32 v248, s98, v167
	v_ashrrev_i32_e32 v249, 31, v248
	v_lshl_add_u64 v[250:251], v[248:249], 2, s[20:21]
	global_load_dword v244, v[250:251], off
	v_or_b32_e32 v248, s98, v171
	v_ashrrev_i32_e32 v249, 31, v248
	v_lshl_add_u64 v[252:253], v[248:249], 2, s[20:21]
	global_load_dword v245, v[252:253], off
	v_or_b32_e32 v248, s98, v172
	v_ashrrev_i32_e32 v249, 31, v248
	v_lshl_add_u64 v[250:251], v[248:249], 2, s[20:21]
	global_load_dword v246, v[250:251], off
	v_or_b32_e32 v248, s98, v173
	v_ashrrev_i32_e32 v249, 31, v248
	v_lshl_add_u64 v[252:253], v[248:249], 2, s[20:21]
	global_load_dword v247, v[252:253], off
	v_or_b32_e32 v158, s74, v167
	v_ashrrev_i32_e32 v159, 31, v158
	s_and_b64 s[6:7], s[18:19], s[78:79]
	s_mov_b64 s[4:5], -1
	s_and_b64 vcc, exec, s[6:7]
	s_waitcnt vmcnt(0)
	v_mul_f32_e32 v5, 0x3e38aa3b, v240
	v_cndmask_b32_e64 v162, v240, v5, s[10:11]
	v_pk_mul_f32 v[8:9], v[8:9], v[162:163] op_sel_hi:[1,0]
	v_pk_mul_f32 v[12:13], v[0:1], v[162:163] op_sel_hi:[1,0]
	v_pk_mul_f32 v[10:11], v[10:11], v[162:163] op_sel_hi:[1,0]
	v_pk_mul_f32 v[14:15], v[2:3], v[162:163] op_sel_hi:[1,0]
	s_cbranch_vccnz .LBB0_301
	s_mov_b64 s[4:5], 0
	v_mov_b32_e32 v7, v15
	v_mov_b32_e32 v6, v14
	v_mov_b32_e32 v5, v13
	v_mov_b32_e32 v4, v12
	v_mov_b32_e32 v3, v11
	v_mov_b32_e32 v2, v10
	v_mov_b32_e32 v1, v9
	v_mov_b32_e32 v0, v8

;     DI void operator()(const pg8::f32x4 (&acc)[2][2][4][2], const pg8::Unit& u, int wr, int wc, int fr, int fq) const {
;     ...
;                 const int tok = u.pm * 256 + ai * 128 + wr * 64 + m * 16 + fr;
;                 const float rs = rstd[tok];
;                 const float rsq = split == 0 ? rs * (0.125f * 1.4426950408889634f) : rs;
;                 const int pos = 16 + (tok & 4095), b = tok >> 12, s = tok & 4095;
; #pragma unroll
;                 for (int bj = 0; bj < 2; ++bj) {
;                     const int nb = nc0 + bj * 128 + wc * 32 + 8 * fq;
;                     float v[8];
; #pragma unroll
;                     for (int j = 0; j < 4; ++j) { v[j] = acc[ai][bj][m][0][j] * rsq; v[4 + j] = acc[ai][bj][m][1][j] * rsq; }
.LBB0_443:
	v_or_b32_e32 v130, s74, v171
	v_ashrrev_i32_e32 v131, 31, v130
	s_and_b64 vcc, exec, s[6:7]
	s_mov_b64 s[58:59], -1
	v_mul_f32_e32 v1, 0x3e38aa3b, v241
	v_cndmask_b32_e64 v134, v241, v1, s[10:11]
	v_pk_mul_f32 v[8:9], v[124:125], v[134:135] op_sel_hi:[1,0]
	v_pk_mul_f32 v[12:13], v[120:121], v[134:135] op_sel_hi:[1,0]
	v_pk_mul_f32 v[10:11], v[126:127], v[134:135] op_sel_hi:[1,0]
	v_pk_mul_f32 v[14:15], v[122:123], v[134:135] op_sel_hi:[1,0]
	s_cbranch_vccnz .LBB0_445
	s_mov_b64 s[58:59], 0
	v_mov_b32_e32 v7, v15
	v_mov_b32_e32 v6, v14
	v_mov_b32_e32 v5, v13
	v_mov_b32_e32 v4, v12
	v_mov_b32_e32 v3, v11
	v_mov_b32_e32 v2, v10
	v_mov_b32_e32 v1, v9
	v_mov_b32_e32 v0, v8

;     DI void operator()(const pg8::f32x4 (&acc)[2][2][4][2], const pg8::Unit& u, int wr, int wc, int fr, int fq) const {
;     ...
;                 const int tok = u.pm * 256 + ai * 128 + wr * 64 + m * 16 + fr;
;                 const float rs = rstd[tok];
;                 const float rsq = split == 0 ? rs * (0.125f * 1.4426950408889634f) : rs;
;                 const int pos = 16 + (tok & 4095), b = tok >> 12, s = tok & 4095;
; #pragma unroll
;                 for (int bj = 0; bj < 2; ++bj) {
;                     const int nb = nc0 + bj * 128 + wc * 32 + 8 * fq;
;                     float v[8];
; #pragma unroll
;                     for (int j = 0; j < 4; ++j) { v[j] = acc[ai][bj][m][0][j] * rsq; v[4 + j] = acc[ai][bj][m][1][j] * rsq; }
.LBB0_577:
	v_or_b32_e32 v112, s74, v172
	v_ashrrev_i32_e32 v113, 31, v112
	s_and_b64 vcc, exec, s[6:7]
	s_mov_b64 s[58:59], -1
	v_mul_f32_e32 v1, 0x3e38aa3b, v242
	v_cndmask_b32_e64 v116, v242, v1, s[10:11]
	v_pk_mul_f32 v[8:9], v[108:109], v[116:117] op_sel_hi:[1,0]
	v_pk_mul_f32 v[12:13], v[104:105], v[116:117] op_sel_hi:[1,0]
	v_pk_mul_f32 v[10:11], v[110:111], v[116:117] op_sel_hi:[1,0]
	v_pk_mul_f32 v[14:15], v[106:107], v[116:117] op_sel_hi:[1,0]
	s_cbranch_vccnz .LBB0_579
	s_mov_b64 s[58:59], 0
	v_mov_b32_e32 v7, v15
	v_mov_b32_e32 v6, v14
	v_mov_b32_e32 v5, v13
	v_mov_b32_e32 v4, v12
	v_mov_b32_e32 v3, v11
	v_mov_b32_e32 v2, v10
	v_mov_b32_e32 v1, v9
	v_mov_b32_e32 v0, v8

;     DI void operator()(const pg8::f32x4 (&acc)[2][2][4][2], const pg8::Unit& u, int wr, int wc, int fr, int fq) const {
;     ...
;                 const int tok = u.pm * 256 + ai * 128 + wr * 64 + m * 16 + fr;
;                 const float rs = rstd[tok];
;                 const float rsq = split == 0 ? rs * (0.125f * 1.4426950408889634f) : rs;
;                 const int pos = 16 + (tok & 4095), b = tok >> 12, s = tok & 4095;
; #pragma unroll
;                 for (int bj = 0; bj < 2; ++bj) {
;                     const int nb = nc0 + bj * 128 + wc * 32 + 8 * fq;
;                     float v[8];
; #pragma unroll
;                     for (int j = 0; j < 4; ++j) { v[j] = acc[ai][bj][m][0][j] * rsq; v[4 + j] = acc[ai][bj][m][1][j] * rsq; }
.LBB0_721:
	v_or_b32_e32 v96, s74, v173
	v_ashrrev_i32_e32 v97, 31, v96
	s_and_b64 vcc, exec, s[6:7]
	s_mov_b64 s[58:59], -1
	v_mul_f32_e32 v1, 0x3e38aa3b, v243
	v_cndmask_b32_e64 v100, v243, v1, s[10:11]
	v_pk_mul_f32 v[8:9], v[92:93], v[100:101] op_sel_hi:[1,0]
	v_pk_mul_f32 v[12:13], v[88:89], v[100:101] op_sel_hi:[1,0]
	v_pk_mul_f32 v[10:11], v[94:95], v[100:101] op_sel_hi:[1,0]
	v_pk_mul_f32 v[14:15], v[90:91], v[100:101] op_sel_hi:[1,0]
	s_cbranch_vccnz .LBB0_723
	s_mov_b64 s[58:59], 0
	v_mov_b32_e32 v7, v15
	v_mov_b32_e32 v6, v14
	v_mov_b32_e32 v5, v13
	v_mov_b32_e32 v4, v12
	v_mov_b32_e32 v3, v11
	v_mov_b32_e32 v2, v10
	v_mov_b32_e32 v1, v9
	v_mov_b32_e32 v0, v8

;     DI void operator()(const pg8::f32x4 (&acc)[2][2][4][2], const pg8::Unit& u, int wr, int wc, int fr, int fq) const {
;     ...
;                 const int tok = u.pm * 256 + ai * 128 + wr * 64 + m * 16 + fr;
;                 const float rs = rstd[tok];
;                 const float rsq = split == 0 ? rs * (0.125f * 1.4426950408889634f) : rs;
;                 const int pos = 16 + (tok & 4095), b = tok >> 12, s = tok & 4095;
; #pragma unroll
;                 for (int bj = 0; bj < 2; ++bj) {
;                     const int nb = nc0 + bj * 128 + wc * 32 + 8 * fq;
;                     float v[8];
; #pragma unroll
;                     for (int j = 0; j < 4; ++j) { v[j] = acc[ai][bj][m][0][j] * rsq; v[4 + j] = acc[ai][bj][m][1][j] * rsq; }
.LBB0_865:
	s_addk_i32 s74, 0x80
	v_or_b32_e32 v80, s74, v167
	v_ashrrev_i32_e32 v81, 31, v80
	s_and_b64 vcc, exec, s[6:7]
	s_mov_b64 s[58:59], -1
	v_mul_f32_e32 v1, 0x3e38aa3b, v244
	v_cndmask_b32_e64 v84, v244, v1, s[10:11]
	v_pk_mul_f32 v[8:9], v[76:77], v[84:85] op_sel_hi:[1,0]
	v_pk_mul_f32 v[12:13], v[72:73], v[84:85] op_sel_hi:[1,0]
	v_pk_mul_f32 v[10:11], v[78:79], v[84:85] op_sel_hi:[1,0]
	v_pk_mul_f32 v[14:15], v[74:75], v[84:85] op_sel_hi:[1,0]
	s_cbranch_vccnz .LBB0_867
	s_mov_b64 s[58:59], 0
	v_mov_b32_e32 v7, v15
	v_mov_b32_e32 v6, v14
	v_mov_b32_e32 v5, v13
	v_mov_b32_e32 v4, v12
	v_mov_b32_e32 v3, v11
	v_mov_b32_e32 v2, v10
	v_mov_b32_e32 v1, v9
	v_mov_b32_e32 v0, v8

;     DI void operator()(const pg8::f32x4 (&acc)[2][2][4][2], const pg8::Unit& u, int wr, int wc, int fr, int fq) const {
;     ...
;                 const int tok = u.pm * 256 + ai * 128 + wr * 64 + m * 16 + fr;
;                 const float rs = rstd[tok];
;                 const float rsq = split == 0 ? rs * (0.125f * 1.4426950408889634f) : rs;
;                 const int pos = 16 + (tok & 4095), b = tok >> 12, s = tok & 4095;
; #pragma unroll
;                 for (int bj = 0; bj < 2; ++bj) {
;                     const int nb = nc0 + bj * 128 + wc * 32 + 8 * fq;
;                     float v[8];
; #pragma unroll
;                     for (int j = 0; j < 4; ++j) { v[j] = acc[ai][bj][m][0][j] * rsq; v[4 + j] = acc[ai][bj][m][1][j] * rsq; }
.LBB0_1009:
	v_or_b32_e32 v64, s74, v171
	v_ashrrev_i32_e32 v65, 31, v64
	s_and_b64 vcc, exec, s[6:7]
	s_mov_b64 s[58:59], -1
	v_mul_f32_e32 v1, 0x3e38aa3b, v245
	v_cndmask_b32_e64 v68, v245, v1, s[10:11]
	v_pk_mul_f32 v[8:9], v[60:61], v[68:69] op_sel_hi:[1,0]
	v_pk_mul_f32 v[12:13], v[56:57], v[68:69] op_sel_hi:[1,0]
	v_pk_mul_f32 v[10:11], v[62:63], v[68:69] op_sel_hi:[1,0]
	v_pk_mul_f32 v[14:15], v[58:59], v[68:69] op_sel_hi:[1,0]
	s_cbranch_vccnz .LBB0_1011
	s_mov_b64 s[58:59], 0
	v_mov_b32_e32 v7, v15
	v_mov_b32_e32 v6, v14
	v_mov_b32_e32 v5, v13
	v_mov_b32_e32 v4, v12
	v_mov_b32_e32 v3, v11
	v_mov_b32_e32 v2, v10
	v_mov_b32_e32 v1, v9
	v_mov_b32_e32 v0, v8

;     DI void operator()(const pg8::f32x4 (&acc)[2][2][4][2], const pg8::Unit& u, int wr, int wc, int fr, int fq) const {
;     ...
;                 const int tok = u.pm * 256 + ai * 128 + wr * 64 + m * 16 + fr;
;                 const float rs = rstd[tok];
;                 const float rsq = split == 0 ? rs * (0.125f * 1.4426950408889634f) : rs;
;                 const int pos = 16 + (tok & 4095), b = tok >> 12, s = tok & 4095;
; #pragma unroll
;                 for (int bj = 0; bj < 2; ++bj) {
;                     const int nb = nc0 + bj * 128 + wc * 32 + 8 * fq;
;                     float v[8];
; #pragma unroll
;                     for (int j = 0; j < 4; ++j) { v[j] = acc[ai][bj][m][0][j] * rsq; v[4 + j] = acc[ai][bj][m][1][j] * rsq; }
.LBB0_1153:
	v_or_b32_e32 v48, s74, v172
	v_ashrrev_i32_e32 v49, 31, v48
	s_and_b64 vcc, exec, s[6:7]
	s_mov_b64 s[58:59], -1
	v_mul_f32_e32 v1, 0x3e38aa3b, v246
	v_cndmask_b32_e64 v52, v246, v1, s[10:11]
	v_pk_mul_f32 v[8:9], v[44:45], v[52:53] op_sel_hi:[1,0]
	v_pk_mul_f32 v[12:13], v[40:41], v[52:53] op_sel_hi:[1,0]
	v_pk_mul_f32 v[10:11], v[46:47], v[52:53] op_sel_hi:[1,0]
	v_pk_mul_f32 v[14:15], v[42:43], v[52:53] op_sel_hi:[1,0]
	s_cbranch_vccnz .LBB0_1155
	s_mov_b64 s[58:59], 0
	v_mov_b32_e32 v7, v15
	v_mov_b32_e32 v6, v14
	v_mov_b32_e32 v5, v13
	v_mov_b32_e32 v4, v12
	v_mov_b32_e32 v3, v11
	v_mov_b32_e32 v2, v10
	v_mov_b32_e32 v1, v9
	v_mov_b32_e32 v0, v8

;     DI void operator()(const pg8::f32x4 (&acc)[2][2][4][2], const pg8::Unit& u, int wr, int wc, int fr, int fq) const {
;     ...
;                 const int tok = u.pm * 256 + ai * 128 + wr * 64 + m * 16 + fr;
;                 const float rs = rstd[tok];
;                 const float rsq = split == 0 ? rs * (0.125f * 1.4426950408889634f) : rs;
;                 const int pos = 16 + (tok & 4095), b = tok >> 12, s = tok & 4095;
; #pragma unroll
;                 for (int bj = 0; bj < 2; ++bj) {
;                     const int nb = nc0 + bj * 128 + wc * 32 + 8 * fq;
;                     float v[8];
; #pragma unroll
;                     for (int j = 0; j < 4; ++j) { v[j] = acc[ai][bj][m][0][j] * rsq; v[4 + j] = acc[ai][bj][m][1][j] * rsq; }
.LBB0_1297:
	v_or_b32_e32 v32, s74, v173
	v_ashrrev_i32_e32 v33, 31, v32
	s_and_b64 vcc, exec, s[6:7]
	v_mul_f32_e32 v1, 0x3e38aa3b, v247
	v_cndmask_b32_e64 v36, v247, v1, s[10:11]
	v_pk_mul_f32 v[8:9], v[28:29], v[36:37] op_sel_hi:[1,0]
	v_pk_mul_f32 v[12:13], v[24:25], v[36:37] op_sel_hi:[1,0]
	v_pk_mul_f32 v[10:11], v[30:31], v[36:37] op_sel_hi:[1,0]
	v_pk_mul_f32 v[14:15], v[26:27], v[36:37] op_sel_hi:[1,0]
	s_mov_b64 s[10:11], -1
	s_cbranch_vccnz .LBB0_1299
	s_mov_b64 s[10:11], 0
	v_mov_b32_e32 v7, v15
	v_mov_b32_e32 v6, v14
	v_mov_b32_e32 v5, v13
	v_mov_b32_e32 v4, v12
	v_mov_b32_e32 v3, v11
	v_mov_b32_e32 v2, v10
	v_mov_b32_e32 v1, v9
	v_mov_b32_e32 v0, v8
